# rmsnorm row loops: wave sum via DPP quad_perm/row_mirror + permlane16/32_swap instead of six ds_bpermute round trips (same adds, same bits)
# baseline (speedup 1.0000x reference)
; DI unsigned pk2(float lo, float hi) { f32x2_t v = {lo, hi}; bf16x2_t b = __builtin_convertvector(v, bf16x2_t); return __builtin_bit_cast(unsigned, b); }
; DI float wave_sum(float v) {
; #pragma unroll
;     for (int o = 1; o < 64; o <<= 1) v += __shfl_xor(v, o);
;     return v;
; }
; DI void p0_xn(KP A, bf16* XN, int grow0, int Tc, int wave, int lane, int G) {
;     ...
;     for (int m = gw; m < Tc; m += NGW) {
;         const int grow = grow0 + m; const float* xr = (grow < 65536) ? kin(A, I_XP) + (size_t)grow * 1024 : kin(A, I_XS) + (size_t)(grow - 65536) * 1024;
;         const f32x4* xv = (const f32x4*)xr + lane; f32x4 v[4]; float s = 0.f;
; #pragma unroll
;         for (int j = 0; j < 4; ++j) { v[j] = xv[64 * j]; s += (v[j].x * v[j].x + v[j].y * v[j].y) + (v[j].z * v[j].z + v[j].w * v[j].w); }
;         const float rs = __builtin_amdgcn_rsqf(wave_sum(s) * (1.0f / 1024.0f) + EPS_);
;         v2u* o8 = (v2u*)(XN + (size_t)m * 1024) + lane;
; #pragma unroll
;         for (int j = 0; j < 4; ++j) { v2u w; w.x = pk2(v[j].x * rs * g[j].x, v[j].y * rs * g[j].y); w.y = pk2(v[j].z * rs * g[j].z, v[j].w * rs * g[j].w); o8[64 * j] = w; }
;     }
.Lxn_a_nopf:
	s_nop 0
	v_pk_mul_f32 v[44:45], v[30:31], v[30:31]
	v_pk_mul_f32 v[46:47], v[28:29], v[28:29]
	s_nop 0
	v_pk_mul_f32 v[48:49], v[34:35], v[34:35]
	v_pk_mul_f32 v[50:51], v[32:33], v[32:33]
	v_pk_mov_b32 v[56:57], v[46:47], v[44:45] op_sel:[1,0]
	v_mov_b32_e32 v47, v45
	v_pk_mov_b32 v[44:45], v[50:51], v[48:49] op_sel:[1,0]
	v_mov_b32_e32 v51, v49
	s_nop 0
	v_mul_f32_e32 v55, v40, v40
	v_mul_f32_e32 v52, v37, v37
	v_mul_f32_e32 v54, v39, v39
	v_pk_add_f32 v[46:47], v[56:57], v[46:47]
	v_pk_add_f32 v[44:45], v[44:45], v[50:51]
	v_mul_f32_e32 v58, v41, v41
	v_mul_f32_e32 v59, v42, v42
	v_mul_f32_e32 v60, v43, v43
	v_pk_fma_f32 v[48:49], v[36:37], v[36:37], v[52:53] op_sel_hi:[1,1,0]
	v_pk_fma_f32 v[52:53], v[38:39], v[38:39], v[54:55] op_sel_hi:[1,1,0]
	v_pk_add_f32 v[46:47], v[46:47], v[46:47] op_sel:[0,1] op_sel_hi:[1,0]
	v_pk_add_f32 v[44:45], v[44:45], v[44:45] op_sel:[0,1] op_sel_hi:[1,0]
	v_mov_b32_e32 v49, v59
	v_mov_b32_e32 v53, v60
	v_mov_b32_e32 v47, v55
	v_mov_b32_e32 v45, v58
	v_pk_add_f32 v[48:49], v[48:49], v[52:53]
	v_pk_add_f32 v[44:45], v[46:47], v[44:45]
	s_nop 0
	v_pk_add_f32 v[44:45], v[44:45], v[48:49]
	s_nop 0
	v_add_f32_e32 v44, v44, v45
	s_nop 1
	v_add_f32_dpp v44, v44, v44 quad_perm:[1,0,3,2] row_mask:0xf bank_mask:0xf
	s_nop 1
	v_add_f32_dpp v44, v44, v44 quad_perm:[2,3,0,1] row_mask:0xf bank_mask:0xf
	s_nop 1
	v_add_f32_dpp v44, v44, v44 row_half_mirror row_mask:0xf bank_mask:0xf
	s_nop 1
	v_add_f32_dpp v44, v44, v44 row_mirror row_mask:0xf bank_mask:0xf
	v_mov_b32_e32 v45, v44
	v_mov_b32_e32 v99, v44
	s_nop 1
	v_permlane16_swap_b32 v45, v99
	v_add_f32_e32 v44, v45, v99
	v_mov_b32_e32 v45, v44
	v_mov_b32_e32 v99, v44
	s_nop 1
	v_permlane32_swap_b32 v45, v99
	v_add_f32_e32 v44, v45, v99
	v_fmamk_f32 v44, v44, 0x3a800000, v27
	v_rsq_f32_e32 v44, v44
	s_nop 0
	v_pk_mul_f32 v[28:29], v[28:29], v[44:45] op_sel_hi:[1,0]
	v_pk_mul_f32 v[30:31], v[30:31], v[44:45] op_sel_hi:[1,0]
	v_pk_mul_f32 v[32:33], v[32:33], v[44:45] op_sel_hi:[1,0]
	v_pk_mul_f32 v[34:35], v[34:35], v[44:45] op_sel_hi:[1,0]
	v_pk_mul_f32 v[36:37], v[36:37], v[44:45] op_sel_hi:[1,0]
	v_pk_mul_f32 v[38:39], v[38:39], v[44:45] op_sel_hi:[1,0]
	v_pk_mul_f32 v[40:41], v[40:41], v[44:45] op_sel_hi:[1,0]
	v_pk_mul_f32 v[42:43], v[42:43], v[44:45] op_sel_hi:[1,0]
	v_pk_mul_f32 v[28:29], v[14:15], v[28:29]
	v_pk_mul_f32 v[30:31], v[16:17], v[30:31]
	v_pk_mul_f32 v[32:33], v[10:11], v[32:33]
	v_pk_mul_f32 v[34:35], v[12:13], v[34:35]
	v_pk_mul_f32 v[36:37], v[6:7], v[36:37]
	v_pk_mul_f32 v[38:39], v[8:9], v[38:39]
	v_pk_mul_f32 v[40:41], v[2:3], v[40:41]
	v_pk_mul_f32 v[42:43], v[4:5], v[42:43]
	v_cvt_pk_bf16_f32 v28, v28, v29
	v_cvt_pk_bf16_f32 v29, v30, v31
	v_cvt_pk_bf16_f32 v30, v32, v33
	v_cvt_pk_bf16_f32 v31, v34, v35
	v_cvt_pk_bf16_f32 v32, v36, v37
	v_cvt_pk_bf16_f32 v33, v38, v39
	v_cvt_pk_bf16_f32 v34, v40, v41
	v_cvt_pk_bf16_f32 v35, v42, v43
	global_store_dwordx2 v[20:21], v[28:29], off offset:-1536
	global_store_dwordx2 v[20:21], v[30:31], off offset:-1024
	global_store_dwordx2 v[20:21], v[32:33], off offset:-512
	global_store_dwordx2 v[20:21], v[34:35], off
	s_cmp_lg_u32 s32, 0
	s_cbranch_scc0 .Lxn_a_done
	s_waitcnt vmcnt(4)
	v_mov_b32_e32 v28, v100
	v_mov_b32_e32 v29, v101
	v_mov_b32_e32 v30, v102
	v_mov_b32_e32 v31, v103
	v_mov_b32_e32 v32, v104
	v_mov_b32_e32 v33, v105
	v_mov_b32_e32 v34, v106
	v_mov_b32_e32 v35, v107
	v_mov_b32_e32 v36, v108
	v_mov_b32_e32 v37, v109
	v_mov_b32_e32 v38, v110
	v_mov_b32_e32 v39, v111
	v_mov_b32_e32 v40, v112
	v_mov_b32_e32 v41, v113
	v_mov_b32_e32 v42, v114
	v_mov_b32_e32 v43, v115
	v_lshl_add_u64 v[20:21], v[20:21], 0, s[4:5]
	s_branch .LBB0_84

; DI unsigned pk2(float lo, float hi) { f32x2_t v = {lo, hi}; bf16x2_t b = __builtin_convertvector(v, bf16x2_t); return __builtin_bit_cast(unsigned, b); }
; DI float wave_sum(float v) {
; #pragma unroll
;     for (int o = 1; o < 64; o <<= 1) v += __shfl_xor(v, o);
;     return v;
; }
; DI void p0_xn(KP A, bf16* XN, int grow0, int Tc, int wave, int lane, int G) {
;     ...
;     for (int m = gw; m < Tc; m += NGW) {
;         const int grow = grow0 + m; const float* xr = (grow < 65536) ? kin(A, I_XP) + (size_t)grow * 1024 : kin(A, I_XS) + (size_t)(grow - 65536) * 1024;
;         const f32x4* xv = (const f32x4*)xr + lane; f32x4 v[4]; float s = 0.f;
; #pragma unroll
;         for (int j = 0; j < 4; ++j) { v[j] = xv[64 * j]; s += (v[j].x * v[j].x + v[j].y * v[j].y) + (v[j].z * v[j].z + v[j].w * v[j].w); }
;         const float rs = __builtin_amdgcn_rsqf(wave_sum(s) * (1.0f / 1024.0f) + EPS_);
;         v2u* o8 = (v2u*)(XN + (size_t)m * 1024) + lane;
; #pragma unroll
;         for (int j = 0; j < 4; ++j) { v2u w; w.x = pk2(v[j].x * rs * g[j].x, v[j].y * rs * g[j].y); w.y = pk2(v[j].z * rs * g[j].z, v[j].w * rs * g[j].w); o8[64 * j] = w; }
;     }
.Lxn_b_nopf:
	s_nop 0
	v_pk_mul_f32 v[42:43], v[28:29], v[28:29]
	v_pk_mul_f32 v[44:45], v[26:27], v[26:27]
	s_nop 0
	v_pk_mul_f32 v[46:47], v[32:33], v[32:33]
	v_pk_mul_f32 v[48:49], v[30:31], v[30:31]
	v_pk_mov_b32 v[54:55], v[44:45], v[42:43] op_sel:[1,0]
	v_mov_b32_e32 v45, v43
	v_pk_mov_b32 v[42:43], v[48:49], v[46:47] op_sel:[1,0]
	v_mov_b32_e32 v49, v47
	s_nop 0
	v_mul_f32_e32 v53, v38, v38
	v_mul_f32_e32 v50, v35, v35
	v_mul_f32_e32 v52, v37, v37
	v_pk_add_f32 v[44:45], v[54:55], v[44:45]
	v_pk_add_f32 v[42:43], v[42:43], v[48:49]
	v_mul_f32_e32 v56, v39, v39
	v_mul_f32_e32 v57, v40, v40
	v_mul_f32_e32 v58, v41, v41
	v_pk_fma_f32 v[46:47], v[34:35], v[34:35], v[50:51] op_sel_hi:[1,1,0]
	v_pk_fma_f32 v[50:51], v[36:37], v[36:37], v[52:53] op_sel_hi:[1,1,0]
	v_pk_add_f32 v[44:45], v[44:45], v[44:45] op_sel:[0,1] op_sel_hi:[1,0]
	v_pk_add_f32 v[42:43], v[42:43], v[42:43] op_sel:[0,1] op_sel_hi:[1,0]
	v_mov_b32_e32 v47, v57
	v_mov_b32_e32 v51, v58
	v_mov_b32_e32 v45, v53
	v_mov_b32_e32 v43, v56
	v_pk_add_f32 v[46:47], v[46:47], v[50:51]
	v_pk_add_f32 v[42:43], v[44:45], v[42:43]
	s_nop 0
	v_pk_add_f32 v[42:43], v[42:43], v[46:47]
	s_nop 0
	v_add_f32_e32 v42, v42, v43
	s_nop 1
	v_add_f32_dpp v42, v42, v42 quad_perm:[1,0,3,2] row_mask:0xf bank_mask:0xf
	s_nop 1
	v_add_f32_dpp v42, v42, v42 quad_perm:[2,3,0,1] row_mask:0xf bank_mask:0xf
	s_nop 1
	v_add_f32_dpp v42, v42, v42 row_half_mirror row_mask:0xf bank_mask:0xf
	s_nop 1
	v_add_f32_dpp v42, v42, v42 row_mirror row_mask:0xf bank_mask:0xf
	v_mov_b32_e32 v43, v42
	v_mov_b32_e32 v99, v42
	s_nop 1
	v_permlane16_swap_b32 v43, v99
	v_add_f32_e32 v42, v43, v99
	v_mov_b32_e32 v43, v42
	v_mov_b32_e32 v99, v42
	s_nop 1
	v_permlane32_swap_b32 v43, v99
	v_add_f32_e32 v42, v43, v99
	v_fmamk_f32 v42, v42, 0x3a800000, v188
	v_rsq_f32_e32 v42, v42
	s_nop 0
	v_pk_mul_f32 v[26:27], v[26:27], v[42:43] op_sel_hi:[1,0]
	v_pk_mul_f32 v[28:29], v[28:29], v[42:43] op_sel_hi:[1,0]
	v_pk_mul_f32 v[30:31], v[30:31], v[42:43] op_sel_hi:[1,0]
	v_pk_mul_f32 v[32:33], v[32:33], v[42:43] op_sel_hi:[1,0]
	v_pk_mul_f32 v[34:35], v[34:35], v[42:43] op_sel_hi:[1,0]
	v_pk_mul_f32 v[36:37], v[36:37], v[42:43] op_sel_hi:[1,0]
	v_pk_mul_f32 v[38:39], v[38:39], v[42:43] op_sel_hi:[1,0]
	v_pk_mul_f32 v[40:41], v[40:41], v[42:43] op_sel_hi:[1,0]
	v_pk_mul_f32 v[26:27], v[14:15], v[26:27]
	v_pk_mul_f32 v[28:29], v[16:17], v[28:29]
	v_pk_mul_f32 v[30:31], v[10:11], v[30:31]
	v_pk_mul_f32 v[32:33], v[12:13], v[32:33]
	v_pk_mul_f32 v[34:35], v[6:7], v[34:35]
	v_pk_mul_f32 v[36:37], v[8:9], v[36:37]
	v_pk_mul_f32 v[38:39], v[2:3], v[38:39]
	v_pk_mul_f32 v[40:41], v[4:5], v[40:41]
	v_cvt_pk_bf16_f32 v26, v26, v27
	v_cvt_pk_bf16_f32 v27, v28, v29
	v_cvt_pk_bf16_f32 v28, v30, v31
	v_cvt_pk_bf16_f32 v29, v32, v33
	v_cvt_pk_bf16_f32 v30, v34, v35
	v_cvt_pk_bf16_f32 v31, v36, v37
	v_cvt_pk_bf16_f32 v32, v38, v39
	v_cvt_pk_bf16_f32 v33, v40, v41
	global_store_dwordx2 v[18:19], v[26:27], off offset:-1024
	global_store_dwordx2 v[18:19], v[28:29], off offset:-512
	global_store_dwordx2 v[18:19], v[30:31], off
	global_store_dwordx2 v[18:19], v[32:33], off offset:512
	s_cmp_lg_u32 s32, 0
	s_cbranch_scc0 .Lxn_b_done
	s_waitcnt vmcnt(4)
	v_mov_b32_e32 v26, v100
	v_mov_b32_e32 v27, v101
	v_mov_b32_e32 v28, v102
	v_mov_b32_e32 v29, v103
	v_mov_b32_e32 v30, v104
	v_mov_b32_e32 v31, v105
	v_mov_b32_e32 v32, v106
	v_mov_b32_e32 v33, v107
	v_mov_b32_e32 v34, v108
	v_mov_b32_e32 v35, v109
	v_mov_b32_e32 v36, v110
	v_mov_b32_e32 v37, v111
	v_mov_b32_e32 v38, v112
	v_mov_b32_e32 v39, v113
	v_mov_b32_e32 v40, v114
	v_mov_b32_e32 v41, v115
	v_lshl_add_u64 v[18:19], v[18:19], 0, s[70:71]
	s_branch .LBB0_1045
